# v15 with the s_setprio pair removed from the attention PV phase
# speedup vs baseline: 1.0243x; 1.0243x over previous
.LatA_h0:
	s_or_b64 exec, exec, s[4:5]
	global_load_dwordx4 v[132:135], v[200:201], off offset:256

	s_waitcnt lgkmcnt(7)
	v_mfma_f32_32x32x16_bf16 v[80:95], v[176:179], v[108:111], v[80:95]
	v_exp_f32_e32 v32, v32
	v_exp_f32_e32 v33, v33
	v_exp_f32_e32 v34, v34
	v_add_f32_e32 v251, v32, v33
	v_cvt_pk_bf16_f32 v48, v48, v49
	v_exp_f32_e32 v35, v35
	v_mfma_f32_32x32x16_bf16 v[64:79], v[140:143], v[112:115], v[64:79]
	v_add_f32_e32 v251, v34, v251
	v_exp_f32_e32 v36, v36
	v_add_f32_e32 v251, v35, v251
	v_cvt_pk_bf16_f32 v49, v50, v51
	v_exp_f32_e32 v37, v37
	v_add_f32_e32 v251, v36, v251
	s_waitcnt lgkmcnt(6)
	v_mfma_f32_32x32x16_bf16 v[80:95], v[160:163], v[112:115], v[80:95]
	v_exp_f32_e32 v38, v38
	v_add_f32_e32 v251, v37, v251
	v_cvt_pk_bf16_f32 v50, v52, v53
	v_exp_f32_e32 v39, v39
	v_add_f32_e32 v251, v38, v251
	v_exp_f32_e32 v40, v40
	v_add_f32_e32 v251, v39, v251
	s_waitcnt lgkmcnt(5)
	v_mfma_f32_32x32x16_bf16 v[64:79], v[148:151], v[116:119], v[64:79]
	v_cvt_pk_bf16_f32 v51, v54, v55
	v_exp_f32_e32 v41, v41
	v_add_f32_e32 v251, v40, v251
	v_exp_f32_e32 v42, v42
	v_add_f32_e32 v251, v41, v251
	v_cvt_pk_bf16_f32 v52, v56, v57
	v_exp_f32_e32 v43, v43
	v_add_u32_e32 v198, v207, v184
	ds_read_b128 v[210:213], v198 offset:44544
	ds_read_b128 v[214:217], v198 offset:39936
	ds_read_b128 v[218:221], v198 offset:39968
	ds_read_b128 v[222:225], v198 offset:44576
	ds_read_b128 v[226:229], v198 offset:40000
	ds_read_b128 v[230:233], v198 offset:44608
	ds_read_b128 v[234:237], v198 offset:40032
	ds_read_b128 v[238:241], v198 offset:44640
	s_waitcnt lgkmcnt(11)
	v_mfma_f32_32x32x16_bf16 v[80:95], v[168:171], v[116:119], v[80:95]
	v_add_f32_e32 v251, v42, v251
	v_exp_f32_e32 v44, v44
	v_add_f32_e32 v251, v43, v251
	v_cvt_pk_bf16_f32 v53, v58, v59
	v_exp_f32_e32 v45, v45
	v_add_f32_e32 v251, v44, v251
	v_mfma_f32_32x32x16_bf16 v[64:79], v[136:139], v[120:123], v[64:79]
	v_exp_f32_e32 v46, v46
	v_add_f32_e32 v251, v45, v251
	v_cvt_pk_bf16_f32 v54, v60, v61
	v_exp_f32_e32 v47, v47
	v_add_f32_e32 v251, v46, v251
	v_add_f32_e32 v251, v47, v251
	v_cvt_pk_bf16_f32 v55, v62, v63
	v_cvt_pk_bf16_f32 v32, v32, v33
	s_waitcnt lgkmcnt(10)
	v_mfma_f32_32x32x16_bf16 v[80:95], v[144:147], v[120:123], v[80:95]
	v_cvt_pk_bf16_f32 v33, v34, v35
	v_cvt_pk_bf16_f32 v34, v36, v37
	v_cvt_pk_bf16_f32 v35, v38, v39
	v_cvt_pk_bf16_f32 v36, v40, v41
	v_cvt_pk_bf16_f32 v37, v42, v43
	v_cvt_pk_bf16_f32 v38, v44, v45
	v_cvt_pk_bf16_f32 v39, v46, v47
	v_add_f32_e32 v195, v195, v251
	v_add_f32_e32 v199, v199, v195
	s_waitcnt lgkmcnt(0)
	s_barrier

	v_add_u32_e32 v197, s6, v204
	s_nop 0
	v_mfma_f32_32x32x16_bf16 v[0:15], v[48:51], v[210:213], v[0:15]
	ds_read_b128 v[172:175], v197
	ds_read_b128 v[152:155], v197 offset:32
	v_mfma_f32_32x32x16_bf16 v[0:15], v[52:55], v[222:225], v[0:15]
	ds_read_b128 v[180:183], v197 offset:6656
	ds_read_b128 v[164:167], v197 offset:6688
	v_mfma_f32_32x32x16_bf16 v[0:15], v[32:35], v[230:233], v[0:15]
	ds_read_b128 v[156:159], v197 offset:64
	ds_read_b128 v[140:143], v197 offset:96
	v_mfma_f32_32x32x16_bf16 v[0:15], v[36:39], v[238:241], v[0:15]
	s_nop 0
	ds_read_b128 v[176:179], v197 offset:6720
	ds_read_b128 v[160:163], v197 offset:6752
	v_mfma_f32_32x32x16_bf16 v[16:31], v[48:51], v[214:217], v[16:31]
	ds_read_b128 v[148:151], v197 offset:128
	ds_read_b128 v[136:139], v197 offset:160
	v_mfma_f32_32x32x16_bf16 v[16:31], v[52:55], v[218:221], v[16:31]
	ds_read_b128 v[168:171], v197 offset:6784
	ds_read_b128 v[144:147], v197 offset:6816
	v_mfma_f32_32x32x16_bf16 v[16:31], v[32:35], v[226:229], v[16:31]
	v_mfma_f32_32x32x16_bf16 v[16:31], v[36:39], v[234:237], v[16:31]
	s_waitcnt lgkmcnt(11)
	v_mfma_f32_32x32x16_bf16 v[48:63], v[172:175], v[100:103], 0
	v_exp_f32_e32 v64, v64
	v_exp_f32_e32 v65, v65
	v_exp_f32_e32 v66, v66
	v_add_f32_e32 v195, v64, v65
	v_exp_f32_e32 v67, v67
	s_waitcnt lgkmcnt(9)
	v_mfma_f32_32x32x16_bf16 v[32:47], v[180:183], v[100:103], 0
	v_add_f32_e32 v195, v66, v195
	v_exp_f32_e32 v68, v68
	v_add_f32_e32 v195, v67, v195
	v_exp_f32_e32 v69, v69
	v_add_f32_e32 v195, v68, v195
	v_exp_f32_e32 v70, v70
	v_add_f32_e32 v195, v69, v195
	v_mfma_f32_32x32x16_bf16 v[48:63], v[152:155], v[104:107], v[48:63]
	v_exp_f32_e32 v71, v71
	v_add_f32_e32 v195, v70, v195
	v_exp_f32_e32 v72, v72
	v_add_f32_e32 v195, v71, v195
	v_exp_f32_e32 v73, v73
	v_add_f32_e32 v195, v72, v195
	s_waitcnt lgkmcnt(8)
	v_mfma_f32_32x32x16_bf16 v[32:47], v[164:167], v[104:107], v[32:47]
	v_exp_f32_e32 v74, v74
	v_add_f32_e32 v195, v73, v195
	v_exp_f32_e32 v75, v75
	v_add_f32_e32 v195, v74, v195
	v_exp_f32_e32 v76, v76
	v_add_f32_e32 v195, v75, v195
	s_waitcnt lgkmcnt(7)
	v_mfma_f32_32x32x16_bf16 v[48:63], v[156:159], v[108:111], v[48:63]
	v_exp_f32_e32 v77, v77
	v_add_f32_e32 v195, v76, v195
	v_exp_f32_e32 v78, v78
	v_add_f32_e32 v195, v77, v195
	v_exp_f32_e32 v79, v79
	v_add_f32_e32 v195, v78, v195
	v_add_f32_e32 v195, v79, v195
	s_add_i32 s4, s91, 1
	s_cmp_lg_u32 s91, 2
	s_cselect_b32 s74, s4, 0
	s_mul_i32 s6, s74, 0x3400
	s_add_i32 s7, s6, 0
	s_add_u32 s98, s98, 0x3000
	s_addc_u32 s99, s99, 0

	v_add_u32_e32 v253, s7, v96
	s_waitcnt vmcnt(1)
	ds_write_b128 v253, v[128:131]
	s_and_saveexec_b64 s[4:5], s[2:3]
	v_add_u32_e32 v253, s7, v185
	ds_write_b128 v253, v[124:127]
	s_or_b64 exec, exec, s[4:5]
	v_lshl_add_u64 v[200:201], s[100:101], 0, v[190:191]

	s_waitcnt vmcnt(0)
	ds_write2_b64 v205, v[132:133], v[134:135] offset0:128 offset1:130
	v_lshl_add_u64 v[128:129], s[98:99], 0, v[188:189]
	s_nop 0
	global_load_dwordx4 v[128:131], v[128:129], off

	s_and_saveexec_b64 s[4:5], s[2:3]
	s_cbranch_execz .LatA_h1
	v_lshl_add_u64 v[124:125], s[98:99], 0, v[186:187]
	s_nop 0
	global_load_dwordx4 v[124:127], v[124:125], off
.LatA_h1:
	s_or_b64 exec, exec, s[4:5]
	global_load_dwordx4 v[132:135], v[200:201], off offset:384

	s_sub_u32 s98, s98, 0x3000
	s_subb_u32 s99, s99, 0

	s_waitcnt lgkmcnt(7)
	v_mfma_f32_32x32x16_bf16 v[32:47], v[176:179], v[108:111], v[32:47]
	v_exp_f32_e32 v80, v80
	v_exp_f32_e32 v81, v81
	v_exp_f32_e32 v82, v82
	v_add_f32_e32 v251, v80, v81
	v_cvt_pk_bf16_f32 v64, v64, v65
	v_exp_f32_e32 v83, v83
	v_mfma_f32_32x32x16_bf16 v[48:63], v[140:143], v[112:115], v[48:63]
	v_add_f32_e32 v251, v82, v251
	v_exp_f32_e32 v84, v84
	v_add_f32_e32 v251, v83, v251
	v_cvt_pk_bf16_f32 v65, v66, v67
	v_exp_f32_e32 v85, v85
	v_add_f32_e32 v251, v84, v251
	s_waitcnt lgkmcnt(6)
	v_mfma_f32_32x32x16_bf16 v[32:47], v[160:163], v[112:115], v[32:47]
	v_exp_f32_e32 v86, v86
	v_add_f32_e32 v251, v85, v251
	v_cvt_pk_bf16_f32 v66, v68, v69
	v_exp_f32_e32 v87, v87
	v_add_f32_e32 v251, v86, v251
	v_exp_f32_e32 v88, v88
	v_add_f32_e32 v251, v87, v251
	s_waitcnt lgkmcnt(5)
	v_mfma_f32_32x32x16_bf16 v[48:63], v[148:151], v[116:119], v[48:63]
	v_cvt_pk_bf16_f32 v67, v70, v71
	v_exp_f32_e32 v89, v89
	v_add_f32_e32 v251, v88, v251
	v_exp_f32_e32 v90, v90
	v_add_f32_e32 v251, v89, v251
	v_cvt_pk_bf16_f32 v68, v72, v73
	v_exp_f32_e32 v91, v91
	v_add_u32_e32 v198, v207, v184
	ds_read_b128 v[210:213], v198 offset:53760
	ds_read_b128 v[214:217], v198 offset:49152
	ds_read_b128 v[218:221], v198 offset:49184
	ds_read_b128 v[222:225], v198 offset:53792
	ds_read_b128 v[226:229], v198 offset:49216
	ds_read_b128 v[230:233], v198 offset:53824
	ds_read_b128 v[234:237], v198 offset:49248
	ds_read_b128 v[238:241], v198 offset:53856
	s_waitcnt lgkmcnt(11)
	v_mfma_f32_32x32x16_bf16 v[32:47], v[168:171], v[116:119], v[32:47]
	v_add_f32_e32 v251, v90, v251
	v_exp_f32_e32 v92, v92
	v_add_f32_e32 v251, v91, v251
	v_cvt_pk_bf16_f32 v69, v74, v75
	v_exp_f32_e32 v93, v93
	v_add_f32_e32 v251, v92, v251
	v_mfma_f32_32x32x16_bf16 v[48:63], v[136:139], v[120:123], v[48:63]
	v_exp_f32_e32 v94, v94
	v_add_f32_e32 v251, v93, v251
	v_cvt_pk_bf16_f32 v70, v76, v77
	v_exp_f32_e32 v95, v95
	v_add_f32_e32 v251, v94, v251
	v_add_f32_e32 v251, v95, v251
	v_cvt_pk_bf16_f32 v71, v78, v79
	v_cvt_pk_bf16_f32 v80, v80, v81
	s_waitcnt lgkmcnt(10)
	v_mfma_f32_32x32x16_bf16 v[32:47], v[144:147], v[120:123], v[32:47]
	v_cvt_pk_bf16_f32 v81, v82, v83
	v_cvt_pk_bf16_f32 v82, v84, v85
	v_cvt_pk_bf16_f32 v83, v86, v87
	v_cvt_pk_bf16_f32 v84, v88, v89
	v_cvt_pk_bf16_f32 v85, v90, v91
	v_cvt_pk_bf16_f32 v86, v92, v93
	v_cvt_pk_bf16_f32 v87, v94, v95
	v_add_f32_e32 v195, v195, v251
	v_add_f32_e32 v199, v199, v195
	s_add_i32 s92, s79, 2
	s_waitcnt lgkmcnt(0)
	s_barrier

	v_add_u32_e32 v197, s6, v204
	s_nop 0
	v_mfma_f32_32x32x16_bf16 v[0:15], v[64:67], v[210:213], v[0:15]
	ds_read_b128 v[172:175], v197
	ds_read_b128 v[152:155], v197 offset:32
	v_mfma_f32_32x32x16_bf16 v[0:15], v[68:71], v[222:225], v[0:15]
	ds_read_b128 v[180:183], v197 offset:6656
	ds_read_b128 v[164:167], v197 offset:6688
	v_mfma_f32_32x32x16_bf16 v[0:15], v[80:83], v[230:233], v[0:15]
	ds_read_b128 v[156:159], v197 offset:64
	ds_read_b128 v[140:143], v197 offset:96
	v_mfma_f32_32x32x16_bf16 v[0:15], v[84:87], v[238:241], v[0:15]
	s_nop 0
	ds_read_b128 v[176:179], v197 offset:6720
	ds_read_b128 v[160:163], v197 offset:6752
	v_mfma_f32_32x32x16_bf16 v[16:31], v[64:67], v[214:217], v[16:31]
	ds_read_b128 v[148:151], v197 offset:128
	ds_read_b128 v[136:139], v197 offset:160
	v_mfma_f32_32x32x16_bf16 v[16:31], v[68:71], v[218:221], v[16:31]
	ds_read_b128 v[168:171], v197 offset:6784
	ds_read_b128 v[144:147], v197 offset:6816
	v_mfma_f32_32x32x16_bf16 v[16:31], v[80:83], v[226:229], v[16:31]
	v_mfma_f32_32x32x16_bf16 v[16:31], v[84:87], v[234:237], v[16:31]
	s_add_i32 s4, s74, 1
	s_cmp_lg_u32 s74, 2
	s_cselect_b32 s91, s4, 0
	s_add_i32 s4, s93, 0x80
	v_lshl_add_u64 v[188:189], v[188:189], 0, s[82:83]
	v_lshl_add_u64 v[186:187], v[186:187], 0, s[82:83]
	v_lshl_add_u64 v[190:191], v[190:191], 0, s[66:67]
	s_cmp_ge_u32 s92, s87
	v_lshl_add_u64 v[192:193], v[98:99], 0, s[66:67]
	s_cbranch_scc1 .LBB0_1049
	v_mov_b64_e32 v[98:99], v[192:193]
	s_mov_b32 s93, s4
	s_mov_b32 s79, s92
	s_branch .LBB0_1039


.LatB_h0:
	s_or_b64 exec, exec, s[4:5]
	global_load_dwordx4 v[132:135], v[200:201], off offset:256

	s_waitcnt lgkmcnt(7)
	v_mfma_f32_32x32x16_bf16 v[80:95], v[176:179], v[108:111], v[80:95]
	v_exp_f32_e32 v32, v32
	v_exp_f32_e32 v33, v33
	v_exp_f32_e32 v34, v34
	v_add_f32_e32 v251, v32, v33
	v_cvt_pk_bf16_f32 v48, v48, v49
	v_exp_f32_e32 v35, v35
	v_mfma_f32_32x32x16_bf16 v[64:79], v[140:143], v[112:115], v[64:79]
	v_add_f32_e32 v251, v34, v251
	v_exp_f32_e32 v36, v36
	v_add_f32_e32 v251, v35, v251
	v_cvt_pk_bf16_f32 v49, v50, v51
	v_exp_f32_e32 v37, v37
	v_add_f32_e32 v251, v36, v251
	s_waitcnt lgkmcnt(6)
	v_mfma_f32_32x32x16_bf16 v[80:95], v[160:163], v[112:115], v[80:95]
	v_exp_f32_e32 v38, v38
	v_add_f32_e32 v251, v37, v251
	v_cvt_pk_bf16_f32 v50, v52, v53
	v_exp_f32_e32 v39, v39
	v_add_f32_e32 v251, v38, v251
	v_exp_f32_e32 v40, v40
	v_add_f32_e32 v251, v39, v251
	s_waitcnt lgkmcnt(5)
	v_mfma_f32_32x32x16_bf16 v[64:79], v[148:151], v[116:119], v[64:79]
	v_cvt_pk_bf16_f32 v51, v54, v55
	v_exp_f32_e32 v41, v41
	v_add_f32_e32 v251, v40, v251
	v_exp_f32_e32 v42, v42
	v_add_f32_e32 v251, v41, v251
	v_cvt_pk_bf16_f32 v52, v56, v57
	v_exp_f32_e32 v43, v43
	v_add_u32_e32 v196, v208, v184
	ds_read_b128 v[212:215], v196 offset:44544
	ds_read_b128 v[216:219], v196 offset:39936
	ds_read_b128 v[220:223], v196 offset:39968
	ds_read_b128 v[224:227], v196 offset:44576
	ds_read_b128 v[228:231], v196 offset:40000
	ds_read_b128 v[232:235], v196 offset:44608
	ds_read_b128 v[236:239], v196 offset:40032
	ds_read_b128 v[240:243], v196 offset:44640
	s_waitcnt lgkmcnt(11)
	v_mfma_f32_32x32x16_bf16 v[80:95], v[168:171], v[116:119], v[80:95]
	v_add_f32_e32 v251, v42, v251
	v_exp_f32_e32 v44, v44
	v_add_f32_e32 v251, v43, v251
	v_cvt_pk_bf16_f32 v53, v58, v59
	v_exp_f32_e32 v45, v45
	v_add_f32_e32 v251, v44, v251
	v_mfma_f32_32x32x16_bf16 v[64:79], v[136:139], v[120:123], v[64:79]
	v_exp_f32_e32 v46, v46
	v_add_f32_e32 v251, v45, v251
	v_cvt_pk_bf16_f32 v54, v60, v61
	v_exp_f32_e32 v47, v47
	v_add_f32_e32 v251, v46, v251
	v_add_f32_e32 v251, v47, v251
	v_cvt_pk_bf16_f32 v55, v62, v63
	v_cvt_pk_bf16_f32 v32, v32, v33
	s_waitcnt lgkmcnt(10)
	v_mfma_f32_32x32x16_bf16 v[80:95], v[144:147], v[120:123], v[80:95]
	v_cvt_pk_bf16_f32 v33, v34, v35
	v_cvt_pk_bf16_f32 v34, v36, v37
	v_cvt_pk_bf16_f32 v35, v38, v39
	v_cvt_pk_bf16_f32 v36, v40, v41
	v_cvt_pk_bf16_f32 v37, v42, v43
	v_cvt_pk_bf16_f32 v38, v44, v45
	v_cvt_pk_bf16_f32 v39, v46, v47
	v_add_f32_e32 v195, v195, v251
	v_add_f32_e32 v198, v198, v195
	s_waitcnt lgkmcnt(0)
	s_barrier

	v_add_u32_e32 v197, s6, v209
	s_nop 0
	v_mfma_f32_32x32x16_bf16 v[0:15], v[48:51], v[212:215], v[0:15]
	ds_read_b128 v[172:175], v197
	ds_read_b128 v[152:155], v197 offset:32
	v_mfma_f32_32x32x16_bf16 v[0:15], v[52:55], v[224:227], v[0:15]
	ds_read_b128 v[180:183], v197 offset:6656
	ds_read_b128 v[164:167], v197 offset:6688
	v_mfma_f32_32x32x16_bf16 v[0:15], v[32:35], v[232:235], v[0:15]
	ds_read_b128 v[156:159], v197 offset:64
	ds_read_b128 v[140:143], v197 offset:96
	v_mfma_f32_32x32x16_bf16 v[0:15], v[36:39], v[240:243], v[0:15]
	s_nop 0
	ds_read_b128 v[176:179], v197 offset:6720
	ds_read_b128 v[160:163], v197 offset:6752
	v_mfma_f32_32x32x16_bf16 v[16:31], v[48:51], v[216:219], v[16:31]
	ds_read_b128 v[148:151], v197 offset:128
	ds_read_b128 v[136:139], v197 offset:160
	v_mfma_f32_32x32x16_bf16 v[16:31], v[52:55], v[220:223], v[16:31]
	ds_read_b128 v[168:171], v197 offset:6784
	ds_read_b128 v[144:147], v197 offset:6816
	v_mfma_f32_32x32x16_bf16 v[16:31], v[32:35], v[228:231], v[16:31]
	v_mfma_f32_32x32x16_bf16 v[16:31], v[36:39], v[236:239], v[16:31]
	s_waitcnt lgkmcnt(11)
	v_mfma_f32_32x32x16_bf16 v[48:63], v[172:175], v[100:103], 0
	v_exp_f32_e32 v64, v64
	v_exp_f32_e32 v65, v65
	v_exp_f32_e32 v66, v66
	v_add_f32_e32 v195, v64, v65
	v_exp_f32_e32 v67, v67
	s_waitcnt lgkmcnt(9)
	v_mfma_f32_32x32x16_bf16 v[32:47], v[180:183], v[100:103], 0
	v_add_f32_e32 v195, v66, v195
	v_exp_f32_e32 v68, v68
	v_add_f32_e32 v195, v67, v195
	v_exp_f32_e32 v69, v69
	v_add_f32_e32 v195, v68, v195
	v_exp_f32_e32 v70, v70
	v_add_f32_e32 v195, v69, v195
	v_mfma_f32_32x32x16_bf16 v[48:63], v[152:155], v[104:107], v[48:63]
	v_exp_f32_e32 v71, v71
	v_add_f32_e32 v195, v70, v195
	v_exp_f32_e32 v72, v72
	v_add_f32_e32 v195, v71, v195
	v_exp_f32_e32 v73, v73
	v_add_f32_e32 v195, v72, v195
	s_waitcnt lgkmcnt(8)
	v_mfma_f32_32x32x16_bf16 v[32:47], v[164:167], v[104:107], v[32:47]
	v_exp_f32_e32 v74, v74
	v_add_f32_e32 v195, v73, v195
	v_exp_f32_e32 v75, v75
	v_add_f32_e32 v195, v74, v195
	v_exp_f32_e32 v76, v76
	v_add_f32_e32 v195, v75, v195
	s_waitcnt lgkmcnt(7)
	v_mfma_f32_32x32x16_bf16 v[48:63], v[156:159], v[108:111], v[48:63]
	v_exp_f32_e32 v77, v77
	v_add_f32_e32 v195, v76, v195
	v_exp_f32_e32 v78, v78
	v_add_f32_e32 v195, v77, v195
	v_exp_f32_e32 v79, v79
	v_add_f32_e32 v195, v78, v195
	v_add_f32_e32 v195, v79, v195
	s_add_i32 s4, s90, 1
	s_cmp_lg_u32 s90, 2
	s_cselect_b32 s68, s4, 0
	s_mul_i32 s6, s68, 0x3400
	s_add_i32 s7, s6, 0
	s_add_u32 s98, s98, 0x3000
	s_addc_u32 s99, s99, 0

	v_add_u32_e32 v253, s7, v96
	s_waitcnt vmcnt(1)
	ds_write_b128 v253, v[128:131]
	s_and_saveexec_b64 s[4:5], s[2:3]
	v_add_u32_e32 v253, s7, v185
	ds_write_b128 v253, v[124:127]
	s_or_b64 exec, exec, s[4:5]
	v_lshl_add_u64 v[200:201], s[100:101], 0, v[204:205]

	s_waitcnt vmcnt(0)
	ds_write2_b64 v211, v[132:133], v[134:135] offset0:128 offset1:130
	v_lshl_add_u64 v[128:129], s[98:99], 0, v[98:99]
	s_nop 0
	global_load_dwordx4 v[128:131], v[128:129], off

	s_and_saveexec_b64 s[4:5], s[2:3]
	s_cbranch_execz .LatB_h1
	v_lshl_add_u64 v[124:125], s[98:99], 0, v[202:203]
	s_nop 0
	global_load_dwordx4 v[124:127], v[124:125], off
.LatB_h1:
	s_or_b64 exec, exec, s[4:5]
	global_load_dwordx4 v[132:135], v[200:201], off offset:384

	s_sub_u32 s98, s98, 0x3000
	s_subb_u32 s99, s99, 0

	s_waitcnt lgkmcnt(7)
	v_mfma_f32_32x32x16_bf16 v[32:47], v[176:179], v[108:111], v[32:47]
	v_exp_f32_e32 v80, v80
	v_exp_f32_e32 v81, v81
	v_exp_f32_e32 v82, v82
	v_add_f32_e32 v251, v80, v81
	v_cvt_pk_bf16_f32 v64, v64, v65
	v_exp_f32_e32 v83, v83
	v_mfma_f32_32x32x16_bf16 v[48:63], v[140:143], v[112:115], v[48:63]
	v_add_f32_e32 v251, v82, v251
	v_exp_f32_e32 v84, v84
	v_add_f32_e32 v251, v83, v251
	v_cvt_pk_bf16_f32 v65, v66, v67
	v_exp_f32_e32 v85, v85
	v_add_f32_e32 v251, v84, v251
	s_waitcnt lgkmcnt(6)
	v_mfma_f32_32x32x16_bf16 v[32:47], v[160:163], v[112:115], v[32:47]
	v_exp_f32_e32 v86, v86
	v_add_f32_e32 v251, v85, v251
	v_cvt_pk_bf16_f32 v66, v68, v69
	v_exp_f32_e32 v87, v87
	v_add_f32_e32 v251, v86, v251
	v_exp_f32_e32 v88, v88
	v_add_f32_e32 v251, v87, v251
	s_waitcnt lgkmcnt(5)
	v_mfma_f32_32x32x16_bf16 v[48:63], v[148:151], v[116:119], v[48:63]
	v_cvt_pk_bf16_f32 v67, v70, v71
	v_exp_f32_e32 v89, v89
	v_add_f32_e32 v251, v88, v251
	v_exp_f32_e32 v90, v90
	v_add_f32_e32 v251, v89, v251
	v_cvt_pk_bf16_f32 v68, v72, v73
	v_exp_f32_e32 v91, v91
	v_add_u32_e32 v196, v208, v184
	ds_read_b128 v[212:215], v196 offset:53760
	ds_read_b128 v[216:219], v196 offset:49152
	ds_read_b128 v[220:223], v196 offset:49184
	ds_read_b128 v[224:227], v196 offset:53792
	ds_read_b128 v[228:231], v196 offset:49216
	ds_read_b128 v[232:235], v196 offset:53824
	ds_read_b128 v[236:239], v196 offset:49248
	ds_read_b128 v[240:243], v196 offset:53856
	s_waitcnt lgkmcnt(11)
	v_mfma_f32_32x32x16_bf16 v[32:47], v[168:171], v[116:119], v[32:47]
	v_add_f32_e32 v251, v90, v251
	v_exp_f32_e32 v92, v92
	v_add_f32_e32 v251, v91, v251
	v_cvt_pk_bf16_f32 v69, v74, v75
	v_exp_f32_e32 v93, v93
	v_add_f32_e32 v251, v92, v251
	v_mfma_f32_32x32x16_bf16 v[48:63], v[136:139], v[120:123], v[48:63]
	v_exp_f32_e32 v94, v94
	v_add_f32_e32 v251, v93, v251
	v_cvt_pk_bf16_f32 v70, v76, v77
	v_exp_f32_e32 v95, v95
	v_add_f32_e32 v251, v94, v251
	v_add_f32_e32 v251, v95, v251
	v_cvt_pk_bf16_f32 v71, v78, v79
	v_cvt_pk_bf16_f32 v80, v80, v81
	s_waitcnt lgkmcnt(10)
	v_mfma_f32_32x32x16_bf16 v[32:47], v[144:147], v[120:123], v[32:47]
	v_cvt_pk_bf16_f32 v81, v82, v83
	v_cvt_pk_bf16_f32 v82, v84, v85
	v_cvt_pk_bf16_f32 v83, v86, v87
	v_cvt_pk_bf16_f32 v84, v88, v89
	v_cvt_pk_bf16_f32 v85, v90, v91
	v_cvt_pk_bf16_f32 v86, v92, v93
	v_cvt_pk_bf16_f32 v87, v94, v95
	v_add_f32_e32 v195, v195, v251
	v_add_f32_e32 v198, v198, v195
	s_add_i32 s40, s40, 2
	s_waitcnt lgkmcnt(0)
	s_barrier

	v_add_u32_e32 v197, s6, v209
	s_nop 0
	v_mfma_f32_32x32x16_bf16 v[0:15], v[64:67], v[212:215], v[0:15]
	ds_read_b128 v[172:175], v197
	ds_read_b128 v[152:155], v197 offset:32
	v_mfma_f32_32x32x16_bf16 v[0:15], v[68:71], v[224:227], v[0:15]
	ds_read_b128 v[180:183], v197 offset:6656
	ds_read_b128 v[164:167], v197 offset:6688
	v_mfma_f32_32x32x16_bf16 v[0:15], v[80:83], v[232:235], v[0:15]
	ds_read_b128 v[156:159], v197 offset:64
	ds_read_b128 v[140:143], v197 offset:96
	v_mfma_f32_32x32x16_bf16 v[0:15], v[84:87], v[240:243], v[0:15]
	s_nop 0
	ds_read_b128 v[176:179], v197 offset:6720
	ds_read_b128 v[160:163], v197 offset:6752
	v_mfma_f32_32x32x16_bf16 v[16:31], v[64:67], v[216:219], v[16:31]
	ds_read_b128 v[148:151], v197 offset:128
	ds_read_b128 v[136:139], v197 offset:160
	v_mfma_f32_32x32x16_bf16 v[16:31], v[68:71], v[220:223], v[16:31]
	ds_read_b128 v[168:171], v197 offset:6784
	ds_read_b128 v[144:147], v197 offset:6816
	v_mfma_f32_32x32x16_bf16 v[16:31], v[80:83], v[228:231], v[16:31]
	v_mfma_f32_32x32x16_bf16 v[16:31], v[84:87], v[236:239], v[16:31]
	s_add_i32 s4, s68, 1
	s_cmp_lg_u32 s68, 2
	s_cselect_b32 s90, s4, 0
	v_lshl_add_u64 v[98:99], v[98:99], 0, s[82:83]
	v_lshl_add_u64 v[202:203], v[202:203], 0, s[82:83]
	s_cmp_ge_u32 s40, s69
	v_lshl_add_u64 v[204:205], v[204:205], 0, s[66:67]
	s_cbranch_scc1 .LBB0_1115
	s_branch .LBB0_1106

